# GEMM phases: accumulator zeroing with 64-bit moves (half the instructions); on top of v16
# speedup vs baseline: 1.0042x; 1.0042x over previous
;   __device__ __forceinline__ bool next(int i,AttnUnit&u)const{ if(i>=2)return false; const int s=vcu&3; u.bh=vcu>>2; u.qb=(i==0)?s:7-s; return true; }
;   __device__ __forceinline__ bool next(int,AttnUnit&u)const{ __syncthreads(); if(threadIdx.x==0)*slot=__hip_atomic_fetch_add(ctr,1u,__ATOMIC_RELAXED,__HIP_MEMORY_SCOPE_AGENT); __syncthreads(); const unsigned v=*slot; if(v>=512u)return false; u.qb=7-(int)(v>>6); u.bh=(int)(v&63u); return true; }
; template <class Epi, class Sched, bool ALIGN_EPI = false, bool SP2 = false>
; __device__ __forceinline__ void gemm_phase(PG8_LAS unsigned char* lds, const Gemm g, const Sched& S, const Epi& E) {
;     ...
;         const bool has_next = S.next(ui + 1, nxt);
;         const char* nA = has_next ? (const char*)g.A + (size_t)nxt.pm * tstep : cA; const char* nB = has_next ? (const char*)g.Bt + (size_t)nxt.pn * tstep : cB;
;         for (int t = 0; t < nt; t += 2) {
;             const bool last = (t == nt - 2);
;             const char* a1 = cA + (size_t)(t + 1) * kstep;
;             const char* a2 = last ? nA : cA + (size_t)(t + 2) * kstep; const char* b2 = last ? nB : cB + (size_t)(t + 2) * kstep;
;             const char* a3 = a2 + kstep; const char* b3 = b2 + kstep;
;     ...
; #pragma unroll
;         for (int a = 0; a < 2; ++a)
; #pragma unroll
;             for (int b = 0; b < 2; ++b)
; #pragma unroll
;                 for (int m = 0; m < 4; ++m)
; #pragma unroll
;                     for (int n = 0; n < 2; ++n) acc[a][b][m][n] = (f32x4){0.f, 0.f, 0.f, 0.f};
;         cur = nxt; cA = nA; cB = nB; ++ui;
.LBB0_101:
	s_ashr_i32 s19, s18, 31
	s_lshl_b64 s[2:3], s[18:19], 19
	s_add_u32 s20, s10, s2
	s_addc_u32 s21, s11, s3
	s_and_b64 s[2:3], s[0:1], exec
	s_cselect_b32 s19, s21, s17
	s_cselect_b32 s44, s20, s16
	s_ashr_i32 s15, s14, 31
	s_lshl_b64 s[2:3], s[14:15], 19
	s_add_u32 s22, s8, s2
	s_addc_u32 s23, s9, s3
	s_and_b64 s[2:3], s[0:1], exec
	s_cselect_b32 s15, s23, s31
	s_cselect_b32 s45, s22, s30
	s_add_u32 s28, s16, 0x40080
	s_addc_u32 s29, s17, 0
	s_add_u32 s30, s30, 0x100
	v_mov_b32_e32 v2, 0
	s_addc_u32 s31, s31, 0
	s_mov_b32 s46, -2
	v_mov_b32_e32 v3, v2
	v_mov_b64_e32 v[4:5], v[2:3]
	v_mov_b64_e32 v[10:11], v[2:3]
	v_mov_b64_e32 v[12:13], v[2:3]
	v_mov_b64_e32 v[18:19], v[2:3]
	v_mov_b64_e32 v[20:21], v[2:3]
	v_mov_b64_e32 v[26:27], v[2:3]
	v_mov_b64_e32 v[28:29], v[2:3]
	v_mov_b64_e32 v[34:35], v[2:3]
	v_mov_b64_e32 v[36:37], v[2:3]
	v_mov_b64_e32 v[42:43], v[2:3]
	v_mov_b64_e32 v[44:45], v[2:3]
	v_mov_b64_e32 v[50:51], v[2:3]
	v_mov_b64_e32 v[52:53], v[2:3]
	v_mov_b64_e32 v[58:59], v[2:3]
	v_mov_b64_e32 v[60:61], v[2:3]
	v_mov_b64_e32 v[6:7], v[2:3]
	v_mov_b64_e32 v[8:9], v[2:3]
	v_mov_b64_e32 v[14:15], v[2:3]
	v_mov_b64_e32 v[16:17], v[2:3]
	v_mov_b64_e32 v[22:23], v[2:3]
	v_mov_b64_e32 v[24:25], v[2:3]
	v_mov_b64_e32 v[30:31], v[2:3]
	v_mov_b64_e32 v[32:33], v[2:3]
	v_mov_b64_e32 v[38:39], v[2:3]
	v_mov_b64_e32 v[40:41], v[2:3]
	v_mov_b64_e32 v[46:47], v[2:3]
	v_mov_b64_e32 v[48:49], v[2:3]
	v_mov_b64_e32 v[54:55], v[2:3]
	v_mov_b64_e32 v[56:57], v[2:3]
	v_mov_b64_e32 v[62:63], v[2:3]
	v_mov_b64_e32 v[64:65], v[2:3]
	v_mov_b64_e32 v[66:67], v[2:3]
	v_mov_b64_e32 v[68:69], v[2:3]
	v_mov_b64_e32 v[74:75], v[2:3]
	v_mov_b64_e32 v[76:77], v[2:3]
	v_mov_b64_e32 v[82:83], v[2:3]
	v_mov_b64_e32 v[84:85], v[2:3]
	v_mov_b64_e32 v[90:91], v[2:3]
	v_mov_b64_e32 v[92:93], v[2:3]
	v_mov_b64_e32 v[98:99], v[2:3]
	v_mov_b64_e32 v[100:101], v[2:3]
	v_mov_b64_e32 v[106:107], v[2:3]
	v_mov_b64_e32 v[108:109], v[2:3]
	v_mov_b64_e32 v[114:115], v[2:3]
	v_mov_b64_e32 v[116:117], v[2:3]
	v_mov_b64_e32 v[122:123], v[2:3]
	v_mov_b64_e32 v[124:125], v[2:3]
	v_mov_b64_e32 v[70:71], v[2:3]
	v_mov_b64_e32 v[72:73], v[2:3]
	v_mov_b64_e32 v[78:79], v[2:3]
	v_mov_b64_e32 v[80:81], v[2:3]
	v_mov_b64_e32 v[86:87], v[2:3]
	v_mov_b64_e32 v[88:89], v[2:3]
	v_mov_b64_e32 v[94:95], v[2:3]
	v_mov_b64_e32 v[96:97], v[2:3]
	v_mov_b64_e32 v[102:103], v[2:3]
	v_mov_b64_e32 v[104:105], v[2:3]
	v_mov_b64_e32 v[110:111], v[2:3]
	v_mov_b64_e32 v[112:113], v[2:3]
	v_mov_b64_e32 v[118:119], v[2:3]
	v_mov_b64_e32 v[120:121], v[2:3]
	v_mov_b64_e32 v[126:127], v[2:3]
	v_mov_b64_e32 v[128:129], v[2:3]

;   __device__ __forceinline__ bool next(int i,AttnUnit&u)const{ if(i>=2)return false; const int s=vcu&3; u.bh=vcu>>2; u.qb=(i==0)?s:7-s; return true; }
;   __device__ __forceinline__ bool next(int,AttnUnit&u)const{ __syncthreads(); if(threadIdx.x==0)*slot=__hip_atomic_fetch_add(ctr,1u,__ATOMIC_RELAXED,__HIP_MEMORY_SCOPE_AGENT); __syncthreads(); const unsigned v=*slot; if(v>=512u)return false; u.qb=7-(int)(v>>6); u.bh=(int)(v&63u); return true; }
; template <class Epi, class Sched, bool ALIGN_EPI = false, bool SP2 = false>
; __device__ __forceinline__ void gemm_phase(PG8_LAS unsigned char* lds, const Gemm g, const Sched& S, const Epi& E) {
;     ...
;         const bool has_next = S.next(ui + 1, nxt);
;         const char* nA = has_next ? (const char*)g.A + (size_t)nxt.pm * tstep : cA; const char* nB = has_next ? (const char*)g.Bt + (size_t)nxt.pn * tstep : cB;
;         for (int t = 0; t < nt; t += 2) {
;             const bool last = (t == nt - 2);
;             const char* a1 = cA + (size_t)(t + 1) * kstep;
;             const char* a2 = last ? nA : cA + (size_t)(t + 2) * kstep; const char* b2 = last ? nB : cB + (size_t)(t + 2) * kstep;
;             const char* a3 = a2 + kstep; const char* b3 = b2 + kstep;
;     ...
; #pragma unroll
;         for (int a = 0; a < 2; ++a)
; #pragma unroll
;             for (int b = 0; b < 2; ++b)
; #pragma unroll
;                 for (int m = 0; m < 4; ++m)
; #pragma unroll
;                     for (int n = 0; n < 2; ++n) acc[a][b][m][n] = (f32x4){0.f, 0.f, 0.f, 0.f};
;         cur = nxt; cA = nA; cB = nB; ++ui;
.LBB0_333:
	s_ashr_i32 s29, s28, 31
	s_lshl_b64 s[2:3], s[28:29], 19
	v_readlane_b32 s14, v245, 57
	v_readlane_b32 s15, v245, 58
	s_add_u32 s30, s14, s2
	s_addc_u32 s31, s15, s3
	s_and_b64 s[2:3], s[4:5], exec
	s_cselect_b32 s7, s31, s11
	s_cselect_b32 s9, s30, s10
	s_ashr_i32 s53, s52, 31
	s_lshl_b64 s[2:3], s[52:53], 19
	s_add_u32 s96, s56, s2
	s_addc_u32 s97, s57, s3
	s_and_b64 s[2:3], s[4:5], exec
	s_cselect_b32 s14, s97, s13
	s_cselect_b32 s15, s96, s12
	s_add_u32 s10, s10, 0x40080
	s_addc_u32 s11, s11, 0
	s_add_u32 s29, s12, 0x100
	v_mov_b32_e32 v2, 0
	s_addc_u32 s36, s13, 0
	s_mov_b32 s37, -2
	v_mov_b32_e32 v3, v2
	v_mov_b64_e32 v[4:5], v[2:3]
	v_mov_b64_e32 v[6:7], v[2:3]
	v_mov_b64_e32 v[8:9], v[2:3]
	v_mov_b64_e32 v[18:19], v[2:3]
	v_mov_b64_e32 v[20:21], v[2:3]
	v_mov_b64_e32 v[22:23], v[2:3]
	v_mov_b64_e32 v[24:25], v[2:3]
	v_mov_b64_e32 v[34:35], v[2:3]
	v_mov_b64_e32 v[36:37], v[2:3]
	v_mov_b64_e32 v[38:39], v[2:3]
	v_mov_b64_e32 v[40:41], v[2:3]
	v_mov_b64_e32 v[50:51], v[2:3]
	v_mov_b64_e32 v[52:53], v[2:3]
	v_mov_b64_e32 v[54:55], v[2:3]
	v_mov_b64_e32 v[56:57], v[2:3]
	v_mov_b64_e32 v[10:11], v[2:3]
	v_mov_b64_e32 v[12:13], v[2:3]
	v_mov_b64_e32 v[14:15], v[2:3]
	v_mov_b64_e32 v[16:17], v[2:3]
	v_mov_b64_e32 v[26:27], v[2:3]
	v_mov_b64_e32 v[28:29], v[2:3]
	v_mov_b64_e32 v[30:31], v[2:3]
	v_mov_b64_e32 v[32:33], v[2:3]
	v_mov_b64_e32 v[42:43], v[2:3]
	v_mov_b64_e32 v[44:45], v[2:3]
	v_mov_b64_e32 v[46:47], v[2:3]
	v_mov_b64_e32 v[48:49], v[2:3]
	v_mov_b64_e32 v[58:59], v[2:3]
	v_mov_b64_e32 v[60:61], v[2:3]
	v_mov_b64_e32 v[62:63], v[2:3]
	v_mov_b64_e32 v[64:65], v[2:3]
	v_mov_b64_e32 v[66:67], v[2:3]
	v_mov_b64_e32 v[68:69], v[2:3]
	v_mov_b64_e32 v[70:71], v[2:3]
	v_mov_b64_e32 v[72:73], v[2:3]
	v_mov_b64_e32 v[82:83], v[2:3]
	v_mov_b64_e32 v[84:85], v[2:3]
	v_mov_b64_e32 v[86:87], v[2:3]
	v_mov_b64_e32 v[88:89], v[2:3]
	v_mov_b64_e32 v[98:99], v[2:3]
	v_mov_b64_e32 v[100:101], v[2:3]
	v_mov_b64_e32 v[102:103], v[2:3]
	v_mov_b64_e32 v[104:105], v[2:3]
	v_mov_b64_e32 v[114:115], v[2:3]
	v_mov_b64_e32 v[116:117], v[2:3]
	v_mov_b64_e32 v[118:119], v[2:3]
	v_mov_b64_e32 v[120:121], v[2:3]
	v_mov_b64_e32 v[74:75], v[2:3]
	v_mov_b64_e32 v[76:77], v[2:3]
	v_mov_b64_e32 v[78:79], v[2:3]
	v_mov_b64_e32 v[80:81], v[2:3]
	v_mov_b64_e32 v[90:91], v[2:3]
	v_mov_b64_e32 v[92:93], v[2:3]
	v_mov_b64_e32 v[94:95], v[2:3]
	v_mov_b64_e32 v[96:97], v[2:3]
	v_mov_b64_e32 v[106:107], v[2:3]
	v_mov_b64_e32 v[108:109], v[2:3]
	v_mov_b64_e32 v[110:111], v[2:3]
	v_mov_b64_e32 v[112:113], v[2:3]
	v_mov_b64_e32 v[122:123], v[2:3]
	v_mov_b64_e32 v[124:125], v[2:3]
	v_mov_b64_e32 v[126:127], v[2:3]
	v_mov_b64_e32 v[128:129], v[2:3]

; #define PG8_STAGE(bufoff, gbase, voff) do { _Pragma("unroll") for (int _i = 0; _i < 2; ++_i) \
;         __builtin_amdgcn_global_load_lds((const unsigned*)((const char*)(gbase) + (voff)[_i]), (PG8_LAS unsigned*)(lds + (bufoff) + ldsw + _i * 8192), 16, 0, 0); } while (0)
; #define PG8_LDA(dst, b, h) do { _Pragma("unroll") for (int m = 0; m < 4; ++m) _Pragma("unroll") for (int k = 0; k < 2; ++k) dst[m][k] = *(const PG8_LAS bf16x8*)(lds + PG8_SA(b, h) + aoff + m * 2048 + k * 1024); } while (0)
; #define PG8_LDB(dst, b, h) do { _Pragma("unroll") for (int n = 0; n < 2; ++n) _Pragma("unroll") for (int k = 0; k < 2; ++k) dst[n][k] = *(const PG8_LAS bf16x8*)(lds + PG8_SB(b, h) + boff + n * 2048 + k * 1024); } while (0)
; #define PG8_MMA(ai, bj, At, Bt) do { __builtin_amdgcn_s_setprio(1); _Pragma("unroll") for (int m = 0; m < 4; ++m) _Pragma("unroll") for (int n = 0; n < 2; ++n) _Pragma("unroll") for (int k = 0; k < 2; ++k) \
;         acc[ai][bj][m][n] = __builtin_amdgcn_mfma_f32_16x16x32_bf16(Bt[n][k], At[m][k], acc[ai][bj][m][n], 0, 0, 0); __builtin_amdgcn_s_setprio(0); } while (0)
; #define PG8_WAIT_V(n) asm volatile("s_waitcnt vmcnt(" #n ")" ::: "memory")
; template <class Epi, class Sched, bool ALIGN_EPI = false, bool SP2 = false>
; __device__ __forceinline__ void gemm_phase(PG8_LAS unsigned char* lds, const Gemm g, const Sched& S, const Epi& E) {
;     ...
;             PG8_LDB(B0, 0, 0); PG8_LDB(B1, 0, 1); PG8_SCHED; PG8_LDA(At, 0, 0); PG8_STAGE(PG8_SA(1, 1), a1 + hstep, voffA);
;             PG8_WAIT_V(8); PG8_WAIT_L(0); PG8_BAR; PG8_MMA(0, 0, At, B0); PG8_MMA(0, 1, At, B1); PG8_BAR; PG8_SCHED;
;             PG8_LDA(At, 0, 1); PG8_STAGE(PG8_SB(0, 0), b2, voffB); PG8_STAGE(PG8_SB(0, 1), b2 + hstep, voffB); PG8_STAGE(PG8_SA(0, 0), a2, voffA);
;             PG8_WAIT_V(8); PG8_WAIT_L(0); PG8_BAR; PG8_MMA(1, 0, At, B0); PG8_MMA(1, 1, At, B1); PG8_BAR; PG8_SCHED;
;             PG8_LDB(B0, 1, 0); PG8_LDB(B1, 1, 1); PG8_SCHED; PG8_LDA(At, 1, 0); PG8_STAGE(PG8_SA(0, 1), a2 + hstep, voffA);
;             PG8_WAIT_V(8); PG8_WAIT_L(0); PG8_BAR; PG8_MMA(0, 0, At, B0); PG8_MMA(0, 1, At, B1); PG8_BAR; PG8_SCHED;
;             PG8_LDA(At, 1, 1); PG8_STAGE(PG8_SB(1, 0), b3, voffB); PG8_STAGE(PG8_SB(1, 1), b3 + hstep, voffB); PG8_STAGE(PG8_SA(1, 0), a3, voffA);
;             PG8_WAIT_V(8); PG8_WAIT_L(0); PG8_BAR; PG8_MMA(1, 0, At, B0); PG8_MMA(1, 1, At, B1); PG8_BAR; PG8_SCHED;
.LBB0_1488:
	v_add_u32_e32 v162, s43, v152
	ds_read_b128 v[154:157], v162
	ds_read_b128 v[158:161], v162 offset:1024
	ds_read_b128 v[166:169], v162 offset:2048
	ds_read_b128 v[170:173], v162 offset:3072
	v_add_u32_e32 v162, s44, v152
	s_add_u32 s2, s0, s40
	ds_read_b128 v[174:177], v162
	ds_read_b128 v[178:181], v162 offset:1024
	ds_read_b128 v[182:185], v162 offset:2048
	ds_read_b128 v[186:189], v162 offset:3072
	s_addc_u32 s3, s1, s41
	s_add_u32 s2, s2, 0x100
	s_addc_u32 s3, s3, 0
	s_add_u32 s51, s46, s40
	s_addc_u32 s52, s47, s41
	s_cmpk_eq_i32 s40, 0x700
	s_cselect_b32 s15, s29, s3
	s_cselect_b32 s14, s48, s2
	s_cselect_b32 s3, s25, s52
	s_cselect_b32 s2, s49, s51
	v_lshl_add_u64 v[162:163], v[146:147], 0, s[40:41]
	s_add_i32 m0, s26, 0xc000
	ds_read_b128 v[190:193], v153
	ds_read_b128 v[194:197], v153 offset:1024
	ds_read_b128 v[198:201], v153 offset:2048
	ds_read_b128 v[202:205], v153 offset:3072
	ds_read_b128 v[206:209], v153 offset:4096
	ds_read_b128 v[210:213], v153 offset:5120
	ds_read_b128 v[214:217], v153 offset:6144
	ds_read_b128 v[218:221], v153 offset:7168
	global_load_lds_dwordx4 v[162:163], off
	v_lshl_add_u64 v[162:163], v[148:149], 0, s[40:41]
	s_add_i32 m0, s26, 0xe000
	s_nop 0
	global_load_lds_dwordx4 v[162:163], off
	s_waitcnt vmcnt(8)
	s_waitcnt lgkmcnt(0)
	s_barrier
	s_setprio 1
	s_waitcnt lgkmcnt(0)
	v_mfma_f32_16x16x32_bf16 v[94:97], v[154:157], v[190:193], v[94:97]
	v_mfma_f32_16x16x32_bf16 v[102:105], v[166:169], v[190:193], v[102:105]
	v_mfma_f32_16x16x32_bf16 v[106:109], v[154:157], v[198:201], v[106:109]
	v_mfma_f32_16x16x32_bf16 v[110:113], v[166:169], v[198:201], v[110:113]
	v_mfma_f32_16x16x32_bf16 v[114:117], v[154:157], v[206:209], v[114:117]
	v_mfma_f32_16x16x32_bf16 v[122:125], v[166:169], v[206:209], v[122:125]
	v_mfma_f32_16x16x32_bf16 v[126:129], v[154:157], v[214:217], v[126:129]
	v_mfma_f32_16x16x32_bf16 v[118:121], v[166:169], v[214:217], v[118:121]
	v_mfma_f32_16x16x32_bf16 v[94:97], v[158:161], v[194:197], v[94:97]
	v_mfma_f32_16x16x32_bf16 v[102:105], v[170:173], v[194:197], v[102:105]
	v_mfma_f32_16x16x32_bf16 v[106:109], v[158:161], v[202:205], v[106:109]
	v_mfma_f32_16x16x32_bf16 v[110:113], v[170:173], v[202:205], v[110:113]
	v_mfma_f32_16x16x32_bf16 v[114:117], v[158:161], v[210:213], v[114:117]
	v_mfma_f32_16x16x32_bf16 v[122:125], v[170:173], v[210:213], v[122:125]
	v_mfma_f32_16x16x32_bf16 v[126:129], v[158:161], v[218:221], v[126:129]
	v_mfma_f32_16x16x32_bf16 v[118:121], v[170:173], v[218:221], v[118:121]
	s_setprio 0
	s_setprio 1
	v_mfma_f32_16x16x32_bf16 v[90:93], v[174:177], v[190:193], v[90:93]
	v_mfma_f32_16x16x32_bf16 v[74:77], v[182:185], v[190:193], v[74:77]
	v_mfma_f32_16x16x32_bf16 v[78:81], v[174:177], v[198:201], v[78:81]
	v_mfma_f32_16x16x32_bf16 v[66:69], v[182:185], v[198:201], v[66:69]
	v_mfma_f32_16x16x32_bf16 v[98:101], v[174:177], v[206:209], v[98:101]
	v_mfma_f32_16x16x32_bf16 v[86:89], v[182:185], v[206:209], v[86:89]
	v_mfma_f32_16x16x32_bf16 v[82:85], v[174:177], v[214:217], v[82:85]
	v_mfma_f32_16x16x32_bf16 v[70:73], v[182:185], v[214:217], v[70:73]
	v_mfma_f32_16x16x32_bf16 v[90:93], v[178:181], v[194:197], v[90:93]
	v_mfma_f32_16x16x32_bf16 v[74:77], v[186:189], v[194:197], v[74:77]
	v_mfma_f32_16x16x32_bf16 v[78:81], v[178:181], v[202:205], v[78:81]
	v_mfma_f32_16x16x32_bf16 v[66:69], v[186:189], v[202:205], v[66:69]
	v_mfma_f32_16x16x32_bf16 v[98:101], v[178:181], v[210:213], v[98:101]
	v_mfma_f32_16x16x32_bf16 v[86:89], v[186:189], v[210:213], v[86:89]
	v_mfma_f32_16x16x32_bf16 v[82:85], v[178:181], v[218:221], v[82:85]
	v_mfma_f32_16x16x32_bf16 v[70:73], v[186:189], v[218:221], v[70:73]
	s_setprio 0
	s_barrier
	s_add_i32 s51, s43, s21
	v_lshl_add_u64 v[162:163], s[2:3], 0, v[132:133]
	s_mov_b32 m0, s51
	ds_read_b128 v[190:193], v153 offset:16384
	ds_read_b128 v[194:197], v153 offset:17408
	ds_read_b128 v[198:201], v153 offset:18432
	ds_read_b128 v[202:205], v153 offset:19456
	ds_read_b128 v[206:209], v153 offset:20480
	ds_read_b128 v[210:213], v153 offset:21504
	ds_read_b128 v[214:217], v153 offset:22528
	ds_read_b128 v[218:221], v153 offset:23552
	global_load_lds_dwordx4 v[162:163], off
	s_add_i32 m0, s51, 0x2000
	s_add_u32 s52, s2, 0x40000
	v_lshl_add_u64 v[222:223], s[2:3], 0, v[136:137]
	s_addc_u32 s53, s3, 0
	s_add_i32 s51, s44, s21
	global_load_lds_dwordx4 v[222:223], off
	v_lshl_add_u64 v[224:225], s[52:53], 0, v[132:133]
	s_mov_b32 m0, s51
	v_lshl_add_u64 v[226:227], s[14:15], 0, v[134:135]
	global_load_lds_dwordx4 v[224:225], off
	v_lshl_add_u64 v[224:225], s[52:53], 0, v[136:137]
	s_add_i32 m0, s51, 0x2000
	s_nop 0
	global_load_lds_dwordx4 v[224:225], off
	v_lshl_add_u64 v[224:225], s[14:15], 0, v[130:131]
	s_mov_b32 m0, s26
	s_nop 0
	global_load_lds_dwordx4 v[224:225], off
	s_mov_b32 m0, s27
	s_nop 0
	global_load_lds_dwordx4 v[226:227], off
	s_waitcnt vmcnt(8)
	s_waitcnt lgkmcnt(0)
	s_barrier
; #define PG8_STAGE(bufoff, gbase, voff) do { _Pragma("unroll") for (int _i = 0; _i < 2; ++_i) \
;         __builtin_amdgcn_global_load_lds((const unsigned*)((const char*)(gbase) + (voff)[_i]), (PG8_LAS unsigned*)(lds + (bufoff) + ldsw + _i * 8192), 16, 0, 0); } while (0)
; #define PG8_LDA(dst, b, h) do { _Pragma("unroll") for (int m = 0; m < 4; ++m) _Pragma("unroll") for (int k = 0; k < 2; ++k) dst[m][k] = *(const PG8_LAS bf16x8*)(lds + PG8_SA(b, h) + aoff + m * 2048 + k * 1024); } while (0)
; #define PG8_LDB(dst, b, h) do { _Pragma("unroll") for (int n = 0; n < 2; ++n) _Pragma("unroll") for (int k = 0; k < 2; ++k) dst[n][k] = *(const PG8_LAS bf16x8*)(lds + PG8_SB(b, h) + boff + n * 2048 + k * 1024); } while (0)
; #define PG8_MMA(ai, bj, At, Bt) do { __builtin_amdgcn_s_setprio(1); _Pragma("unroll") for (int m = 0; m < 4; ++m) _Pragma("unroll") for (int n = 0; n < 2; ++n) _Pragma("unroll") for (int k = 0; k < 2; ++k) \
;         acc[ai][bj][m][n] = __builtin_amdgcn_mfma_f32_16x16x32_bf16(Bt[n][k], At[m][k], acc[ai][bj][m][n], 0, 0, 0); __builtin_amdgcn_s_setprio(0); } while (0)
; #define PG8_WAIT_V(n) asm volatile("s_waitcnt vmcnt(" #n ")" ::: "memory")
; template <class Epi, class Sched, bool ALIGN_EPI = false, bool SP2 = false>
; __device__ __forceinline__ void gemm_phase(PG8_LAS unsigned char* lds, const Gemm g, const Sched& S, const Epi& E) {
;     ...
;             PG8_LDB(B0, 0, 0); PG8_LDB(B1, 0, 1); PG8_SCHED; PG8_LDA(At, 0, 0); PG8_STAGE(PG8_SA(1, 1), a1 + hstep, voffA);
;             PG8_WAIT_V(8); PG8_WAIT_L(0); PG8_BAR; PG8_MMA(0, 0, At, B0); PG8_MMA(0, 1, At, B1); PG8_BAR; PG8_SCHED;
;             PG8_LDA(At, 0, 1); PG8_STAGE(PG8_SB(0, 0), b2, voffB); PG8_STAGE(PG8_SB(0, 1), b2 + hstep, voffB); PG8_STAGE(PG8_SA(0, 0), a2, voffA);
;             PG8_WAIT_V(8); PG8_WAIT_L(0); PG8_BAR; PG8_MMA(1, 0, At, B0); PG8_MMA(1, 1, At, B1); PG8_BAR; PG8_SCHED;
;             PG8_LDB(B0, 1, 0); PG8_LDB(B1, 1, 1); PG8_SCHED; PG8_LDA(At, 1, 0); PG8_STAGE(PG8_SA(0, 1), a2 + hstep, voffA);
;             PG8_WAIT_V(8); PG8_WAIT_L(0); PG8_BAR; PG8_MMA(0, 0, At, B0); PG8_MMA(0, 1, At, B1); PG8_BAR; PG8_SCHED;
;             PG8_LDA(At, 1, 1); PG8_STAGE(PG8_SB(1, 0), b3, voffB); PG8_STAGE(PG8_SB(1, 1), b3 + hstep, voffB); PG8_STAGE(PG8_SA(1, 0), a3, voffA);
;             PG8_WAIT_V(8); PG8_WAIT_L(0); PG8_BAR; PG8_MMA(1, 0, At, B0); PG8_MMA(1, 1, At, B1); PG8_BAR; PG8_SCHED;
	s_setprio 1
	s_waitcnt lgkmcnt(0)
	v_mfma_f32_16x16x32_bf16 v[62:65], v[154:157], v[190:193], v[62:65]
	v_mfma_f32_16x16x32_bf16 v[58:61], v[166:169], v[190:193], v[58:61]
	v_mfma_f32_16x16x32_bf16 v[46:49], v[154:157], v[198:201], v[46:49]
	v_mfma_f32_16x16x32_bf16 v[42:45], v[166:169], v[198:201], v[42:45]
	v_mfma_f32_16x16x32_bf16 v[30:33], v[154:157], v[206:209], v[30:33]
	v_mfma_f32_16x16x32_bf16 v[26:29], v[166:169], v[206:209], v[26:29]
	v_mfma_f32_16x16x32_bf16 v[14:17], v[154:157], v[214:217], v[14:17]
	v_mfma_f32_16x16x32_bf16 v[10:13], v[166:169], v[214:217], v[10:13]
	v_mfma_f32_16x16x32_bf16 v[62:65], v[158:161], v[194:197], v[62:65]
	v_mfma_f32_16x16x32_bf16 v[58:61], v[170:173], v[194:197], v[58:61]
	v_mfma_f32_16x16x32_bf16 v[46:49], v[158:161], v[202:205], v[46:49]
	v_mfma_f32_16x16x32_bf16 v[42:45], v[170:173], v[202:205], v[42:45]
	v_mfma_f32_16x16x32_bf16 v[30:33], v[158:161], v[210:213], v[30:33]
	v_mfma_f32_16x16x32_bf16 v[26:29], v[170:173], v[210:213], v[26:29]
	v_mfma_f32_16x16x32_bf16 v[14:17], v[158:161], v[218:221], v[14:17]
	v_mfma_f32_16x16x32_bf16 v[10:13], v[170:173], v[218:221], v[10:13]
	s_setprio 0
	s_setprio 1
	v_mfma_f32_16x16x32_bf16 v[54:57], v[174:177], v[190:193], v[54:57]
	v_mfma_f32_16x16x32_bf16 v[50:53], v[182:185], v[190:193], v[50:53]
	v_mfma_f32_16x16x32_bf16 v[38:41], v[174:177], v[198:201], v[38:41]
	v_mfma_f32_16x16x32_bf16 v[34:37], v[182:185], v[198:201], v[34:37]
	v_mfma_f32_16x16x32_bf16 v[22:25], v[174:177], v[206:209], v[22:25]
	v_mfma_f32_16x16x32_bf16 v[18:21], v[182:185], v[206:209], v[18:21]
	v_mfma_f32_16x16x32_bf16 v[6:9], v[174:177], v[214:217], v[6:9]
	v_mfma_f32_16x16x32_bf16 v[2:5], v[182:185], v[214:217], v[2:5]
	v_mfma_f32_16x16x32_bf16 v[54:57], v[178:181], v[194:197], v[54:57]
	v_mfma_f32_16x16x32_bf16 v[50:53], v[186:189], v[194:197], v[50:53]
	v_mfma_f32_16x16x32_bf16 v[38:41], v[178:181], v[202:205], v[38:41]
	v_mfma_f32_16x16x32_bf16 v[34:37], v[186:189], v[202:205], v[34:37]
	v_mfma_f32_16x16x32_bf16 v[22:25], v[178:181], v[210:213], v[22:25]
	v_mfma_f32_16x16x32_bf16 v[18:21], v[186:189], v[210:213], v[18:21]
	v_mfma_f32_16x16x32_bf16 v[6:9], v[178:181], v[218:221], v[6:9]
	v_mfma_f32_16x16x32_bf16 v[2:5], v[186:189], v[218:221], v[2:5]
	s_setprio 0
	s_barrier
	s_add_i32 s51, 0, 0x18000
	v_add_u32_e32 v165, s51, v152
	s_add_i32 s52, 0, 0x1c000
	ds_read_b128 v[154:157], v165
	ds_read_b128 v[158:161], v165 offset:1024
	ds_read_b128 v[166:169], v165 offset:2048
	ds_read_b128 v[170:173], v165 offset:3072
	v_add_u32_e32 v165, s52, v152
	ds_read_b128 v[174:177], v165
	ds_read_b128 v[178:181], v165 offset:1024
	ds_read_b128 v[182:185], v165 offset:2048
	ds_read_b128 v[186:189], v165 offset:3072
	s_add_u32 s14, s14, 0x40000
	s_addc_u32 s15, s15, 0
	s_mov_b32 m0, s33
	v_lshl_add_u64 v[228:229], s[14:15], 0, v[130:131]
	ds_read_b128 v[190:193], v153 offset:32768
	ds_read_b128 v[194:197], v153 offset:33792
	ds_read_b128 v[198:201], v153 offset:34816
	ds_read_b128 v[202:205], v153 offset:35840
	ds_read_b128 v[206:209], v153 offset:36864
	ds_read_b128 v[210:213], v153 offset:37888
	ds_read_b128 v[214:217], v153 offset:38912
	ds_read_b128 v[218:221], v153 offset:39936
	global_load_lds_dwordx4 v[228:229], off
	v_lshl_add_u64 v[228:229], s[14:15], 0, v[134:135]
	s_mov_b32 m0, s34
	s_nop 0
	global_load_lds_dwordx4 v[228:229], off
	s_waitcnt vmcnt(8)
	s_waitcnt lgkmcnt(0)
	s_barrier
	s_setprio 1
	s_waitcnt lgkmcnt(0)
	v_mfma_f32_16x16x32_bf16 v[94:97], v[154:157], v[190:193], v[94:97]
	v_mfma_f32_16x16x32_bf16 v[102:105], v[166:169], v[190:193], v[102:105]
	v_mfma_f32_16x16x32_bf16 v[106:109], v[154:157], v[198:201], v[106:109]
	v_mfma_f32_16x16x32_bf16 v[110:113], v[166:169], v[198:201], v[110:113]
	v_mfma_f32_16x16x32_bf16 v[114:117], v[154:157], v[206:209], v[114:117]
	v_mfma_f32_16x16x32_bf16 v[122:125], v[166:169], v[206:209], v[122:125]
	v_mfma_f32_16x16x32_bf16 v[126:129], v[154:157], v[214:217], v[126:129]
	v_mfma_f32_16x16x32_bf16 v[118:121], v[166:169], v[214:217], v[118:121]
	v_mfma_f32_16x16x32_bf16 v[94:97], v[158:161], v[194:197], v[94:97]
	v_mfma_f32_16x16x32_bf16 v[102:105], v[170:173], v[194:197], v[102:105]
	v_mfma_f32_16x16x32_bf16 v[106:109], v[158:161], v[202:205], v[106:109]
	v_mfma_f32_16x16x32_bf16 v[110:113], v[170:173], v[202:205], v[110:113]
	v_mfma_f32_16x16x32_bf16 v[114:117], v[158:161], v[210:213], v[114:117]
	v_mfma_f32_16x16x32_bf16 v[122:125], v[170:173], v[210:213], v[122:125]
	v_mfma_f32_16x16x32_bf16 v[126:129], v[158:161], v[218:221], v[126:129]
	v_mfma_f32_16x16x32_bf16 v[118:121], v[170:173], v[218:221], v[118:121]
	s_setprio 0
	s_setprio 1
	v_mfma_f32_16x16x32_bf16 v[90:93], v[174:177], v[190:193], v[90:93]
	v_mfma_f32_16x16x32_bf16 v[74:77], v[182:185], v[190:193], v[74:77]
	v_mfma_f32_16x16x32_bf16 v[78:81], v[174:177], v[198:201], v[78:81]
	v_mfma_f32_16x16x32_bf16 v[66:69], v[182:185], v[198:201], v[66:69]
	v_mfma_f32_16x16x32_bf16 v[98:101], v[174:177], v[206:209], v[98:101]
	v_mfma_f32_16x16x32_bf16 v[86:89], v[182:185], v[206:209], v[86:89]
	v_mfma_f32_16x16x32_bf16 v[82:85], v[174:177], v[214:217], v[82:85]
	v_mfma_f32_16x16x32_bf16 v[70:73], v[182:185], v[214:217], v[70:73]
	v_mfma_f32_16x16x32_bf16 v[90:93], v[178:181], v[194:197], v[90:93]
	v_mfma_f32_16x16x32_bf16 v[74:77], v[186:189], v[194:197], v[74:77]
	v_mfma_f32_16x16x32_bf16 v[78:81], v[178:181], v[202:205], v[78:81]
	v_mfma_f32_16x16x32_bf16 v[66:69], v[186:189], v[202:205], v[66:69]
	v_mfma_f32_16x16x32_bf16 v[98:101], v[178:181], v[210:213], v[98:101]
	v_mfma_f32_16x16x32_bf16 v[86:89], v[186:189], v[210:213], v[86:89]
	v_mfma_f32_16x16x32_bf16 v[82:85], v[178:181], v[218:221], v[82:85]
	v_mfma_f32_16x16x32_bf16 v[70:73], v[186:189], v[218:221], v[70:73]
	s_setprio 0
	s_barrier
; #define PG8_STAGE(bufoff, gbase, voff) do { _Pragma("unroll") for (int _i = 0; _i < 2; ++_i) \
;         __builtin_amdgcn_global_load_lds((const unsigned*)((const char*)(gbase) + (voff)[_i]), (PG8_LAS unsigned*)(lds + (bufoff) + ldsw + _i * 8192), 16, 0, 0); } while (0)
; #define PG8_LDA(dst, b, h) do { _Pragma("unroll") for (int m = 0; m < 4; ++m) _Pragma("unroll") for (int k = 0; k < 2; ++k) dst[m][k] = *(const PG8_LAS bf16x8*)(lds + PG8_SA(b, h) + aoff + m * 2048 + k * 1024); } while (0)
; #define PG8_LDB(dst, b, h) do { _Pragma("unroll") for (int n = 0; n < 2; ++n) _Pragma("unroll") for (int k = 0; k < 2; ++k) dst[n][k] = *(const PG8_LAS bf16x8*)(lds + PG8_SB(b, h) + boff + n * 2048 + k * 1024); } while (0)
; #define PG8_WAIT_V(n) asm volatile("s_waitcnt vmcnt(" #n ")" ::: "memory")
; #define PG8_WAIT_L(n) asm volatile("s_waitcnt lgkmcnt(" #n ")" ::: "memory")
; #define PG8_BAR __builtin_amdgcn_s_barrier()
; template <class Epi, class Sched, bool ALIGN_EPI = false, bool SP2 = false>
; __device__ __forceinline__ void gemm_phase(PG8_LAS unsigned char* lds, const Gemm g, const Sched& S, const Epi& E) {
;     ...
;             PG8_WAIT_V(8); PG8_WAIT_L(0); PG8_BAR; PG8_MMA(0, 0, At, B0); PG8_MMA(0, 1, At, B1); PG8_BAR; PG8_SCHED;
;             PG8_LDA(At, 0, 1); PG8_STAGE(PG8_SB(0, 0), b2, voffB); PG8_STAGE(PG8_SB(0, 1), b2 + hstep, voffB); PG8_STAGE(PG8_SA(0, 0), a2, voffA);
;             PG8_WAIT_V(8); PG8_WAIT_L(0); PG8_BAR; PG8_MMA(1, 0, At, B0); PG8_MMA(1, 1, At, B1); PG8_BAR; PG8_SCHED;
;             PG8_LDB(B0, 1, 0); PG8_LDB(B1, 1, 1); PG8_SCHED; PG8_LDA(At, 1, 0); PG8_STAGE(PG8_SA(0, 1), a2 + hstep, voffA);
;             PG8_WAIT_V(8); PG8_WAIT_L(0); PG8_BAR; PG8_MMA(0, 0, At, B0); PG8_MMA(0, 1, At, B1); PG8_BAR; PG8_SCHED;
;             PG8_LDA(At, 1, 1); PG8_STAGE(PG8_SB(1, 0), b3, voffB); PG8_STAGE(PG8_SB(1, 1), b3 + hstep, voffB); PG8_STAGE(PG8_SA(1, 0), a3, voffA);
;             PG8_WAIT_V(8); PG8_WAIT_L(0); PG8_BAR; PG8_MMA(1, 0, At, B0); PG8_MMA(1, 1, At, B1); PG8_BAR; PG8_SCHED;
;     ...
;         if (!has_next) break;
; #pragma unroll
;         for (int a = 0; a < 2; ++a)
; #pragma unroll
;             for (int b = 0; b < 2; ++b)
; #pragma unroll
;                 for (int m = 0; m < 4; ++m)
; #pragma unroll
;                     for (int n = 0; n < 2; ++n) acc[a][b][m][n] = (f32x4){0.f, 0.f, 0.f, 0.f};
;         cur = nxt; cA = nA; cB = nB; ++ui;
	s_add_i32 s14, s51, s21
	v_lshl_add_u64 v[162:163], v[162:163], 0, s[22:23]
	s_mov_b32 m0, s14
	ds_read_b128 v[190:193], v153 offset:49152
	ds_read_b128 v[194:197], v153 offset:50176
	ds_read_b128 v[198:201], v153 offset:51200
	ds_read_b128 v[202:205], v153 offset:52224
	ds_read_b128 v[206:209], v153 offset:53248
	ds_read_b128 v[210:213], v153 offset:54272
	ds_read_b128 v[214:217], v153 offset:55296
	ds_read_b128 v[218:221], v153 offset:56320
	global_load_lds_dwordx4 v[162:163], off
	s_add_i32 m0, s14, 0x2000
	s_add_u32 s2, s2, 0x40080
	v_lshl_add_u64 v[162:163], v[222:223], 0, s[22:23]
	s_addc_u32 s3, s3, 0
	s_add_i32 s14, s52, s21
	global_load_lds_dwordx4 v[162:163], off
	v_lshl_add_u64 v[162:163], s[2:3], 0, v[132:133]
	s_mov_b32 m0, s14
	s_nop 0
	global_load_lds_dwordx4 v[162:163], off
	v_lshl_add_u64 v[162:163], s[2:3], 0, v[136:137]
	s_add_i32 m0, s14, 0x2000
	s_nop 0
	global_load_lds_dwordx4 v[162:163], off
	v_lshl_add_u64 v[162:163], v[224:225], 0, s[22:23]
	s_mov_b32 m0, s37
	s_nop 0
	global_load_lds_dwordx4 v[162:163], off
	v_lshl_add_u64 v[162:163], v[226:227], 0, s[22:23]
	s_mov_b32 m0, s42
	s_nop 0
	global_load_lds_dwordx4 v[162:163], off
	s_waitcnt vmcnt(8)
	s_waitcnt lgkmcnt(0)
	s_barrier
	s_setprio 1
	s_waitcnt lgkmcnt(0)
	v_mfma_f32_16x16x32_bf16 v[62:65], v[154:157], v[190:193], v[62:65]
	v_mfma_f32_16x16x32_bf16 v[58:61], v[166:169], v[190:193], v[58:61]
	v_mfma_f32_16x16x32_bf16 v[46:49], v[154:157], v[198:201], v[46:49]
	v_mfma_f32_16x16x32_bf16 v[42:45], v[166:169], v[198:201], v[42:45]
	v_mfma_f32_16x16x32_bf16 v[30:33], v[154:157], v[206:209], v[30:33]
	v_mfma_f32_16x16x32_bf16 v[26:29], v[166:169], v[206:209], v[26:29]
	v_mfma_f32_16x16x32_bf16 v[14:17], v[154:157], v[214:217], v[14:17]
	v_mfma_f32_16x16x32_bf16 v[10:13], v[166:169], v[214:217], v[10:13]
	v_mfma_f32_16x16x32_bf16 v[62:65], v[158:161], v[194:197], v[62:65]
	v_mfma_f32_16x16x32_bf16 v[58:61], v[170:173], v[194:197], v[58:61]
	v_mfma_f32_16x16x32_bf16 v[46:49], v[158:161], v[202:205], v[46:49]
	v_mfma_f32_16x16x32_bf16 v[42:45], v[170:173], v[202:205], v[42:45]
	v_mfma_f32_16x16x32_bf16 v[30:33], v[158:161], v[210:213], v[30:33]
	v_mfma_f32_16x16x32_bf16 v[26:29], v[170:173], v[210:213], v[26:29]
	v_mfma_f32_16x16x32_bf16 v[14:17], v[158:161], v[218:221], v[14:17]
	v_mfma_f32_16x16x32_bf16 v[10:13], v[170:173], v[218:221], v[10:13]
	s_setprio 0
	s_setprio 1
	v_mfma_f32_16x16x32_bf16 v[54:57], v[174:177], v[190:193], v[54:57]
	v_mfma_f32_16x16x32_bf16 v[50:53], v[182:185], v[190:193], v[50:53]
	v_mfma_f32_16x16x32_bf16 v[38:41], v[174:177], v[198:201], v[38:41]
	v_mfma_f32_16x16x32_bf16 v[34:37], v[182:185], v[198:201], v[34:37]
	v_mfma_f32_16x16x32_bf16 v[22:25], v[174:177], v[206:209], v[22:25]
	v_mfma_f32_16x16x32_bf16 v[18:21], v[182:185], v[206:209], v[18:21]
	v_mfma_f32_16x16x32_bf16 v[6:9], v[174:177], v[214:217], v[6:9]
	v_mfma_f32_16x16x32_bf16 v[2:5], v[182:185], v[214:217], v[2:5]
	v_mfma_f32_16x16x32_bf16 v[54:57], v[178:181], v[194:197], v[54:57]
	v_mfma_f32_16x16x32_bf16 v[50:53], v[186:189], v[194:197], v[50:53]
	v_mfma_f32_16x16x32_bf16 v[38:41], v[178:181], v[202:205], v[38:41]
	v_mfma_f32_16x16x32_bf16 v[34:37], v[186:189], v[202:205], v[34:37]
	v_mfma_f32_16x16x32_bf16 v[22:25], v[178:181], v[210:213], v[22:25]
	v_mfma_f32_16x16x32_bf16 v[18:21], v[186:189], v[210:213], v[18:21]
	v_mfma_f32_16x16x32_bf16 v[6:9], v[178:181], v[218:221], v[6:9]
	v_mfma_f32_16x16x32_bf16 v[2:5], v[186:189], v[218:221], v[2:5]
	s_setprio 0
	s_barrier
	s_add_i32 s50, s50, 2
	s_add_u32 s40, s40, 0x100
	s_addc_u32 s41, s41, 0
	s_cmp_gt_u32 s50, 13
	s_cbranch_scc0 .LBB0_1488
	s_add_u32 s2, s46, 0xffffff00
	s_addc_u32 s3, s47, -1
	s_andn2_b64 vcc, exec, s[8:9]
	s_cbranch_vccnz .LBB0_1491
	v_mov_b32_e32 v2, 0
	s_mov_b32 s20, s24
	s_mov_b32 s12, s28
	s_mov_b64 s[0:1], s[38:39]
	s_mov_b32 s36, s45
	v_mov_b32_e32 v3, v2
	v_mov_b64_e32 v[4:5], v[2:3]
	v_mov_b64_e32 v[6:7], v[2:3]
	v_mov_b64_e32 v[8:9], v[2:3]
	v_mov_b64_e32 v[18:19], v[2:3]
	v_mov_b64_e32 v[20:21], v[2:3]
	v_mov_b64_e32 v[22:23], v[2:3]
	v_mov_b64_e32 v[24:25], v[2:3]
	v_mov_b64_e32 v[34:35], v[2:3]
	v_mov_b64_e32 v[36:37], v[2:3]
	v_mov_b64_e32 v[38:39], v[2:3]
	v_mov_b64_e32 v[40:41], v[2:3]
	v_mov_b64_e32 v[50:51], v[2:3]
	v_mov_b64_e32 v[52:53], v[2:3]
	v_mov_b64_e32 v[54:55], v[2:3]
	v_mov_b64_e32 v[56:57], v[2:3]
	v_mov_b64_e32 v[10:11], v[2:3]
	v_mov_b64_e32 v[12:13], v[2:3]
	v_mov_b64_e32 v[14:15], v[2:3]
	v_mov_b64_e32 v[16:17], v[2:3]
	v_mov_b64_e32 v[26:27], v[2:3]
	v_mov_b64_e32 v[28:29], v[2:3]
	v_mov_b64_e32 v[30:31], v[2:3]
	v_mov_b64_e32 v[32:33], v[2:3]
	v_mov_b64_e32 v[42:43], v[2:3]
	v_mov_b64_e32 v[44:45], v[2:3]
	v_mov_b64_e32 v[46:47], v[2:3]
	v_mov_b64_e32 v[48:49], v[2:3]
	v_mov_b64_e32 v[58:59], v[2:3]
	v_mov_b64_e32 v[60:61], v[2:3]
	v_mov_b64_e32 v[62:63], v[2:3]
	v_mov_b64_e32 v[64:65], v[2:3]
	v_mov_b64_e32 v[70:71], v[2:3]
	v_mov_b64_e32 v[72:73], v[2:3]
	v_mov_b64_e32 v[82:83], v[2:3]
	v_mov_b64_e32 v[84:85], v[2:3]
	v_mov_b64_e32 v[86:87], v[2:3]
	v_mov_b64_e32 v[88:89], v[2:3]
	v_mov_b64_e32 v[98:99], v[2:3]
	v_mov_b64_e32 v[100:101], v[2:3]
	v_mov_b64_e32 v[66:67], v[2:3]
	v_mov_b64_e32 v[68:69], v[2:3]
	v_mov_b64_e32 v[78:79], v[2:3]
	v_mov_b64_e32 v[80:81], v[2:3]
	v_mov_b64_e32 v[74:75], v[2:3]
	v_mov_b64_e32 v[76:77], v[2:3]
	v_mov_b64_e32 v[90:91], v[2:3]
	v_mov_b64_e32 v[92:93], v[2:3]
	v_mov_b64_e32 v[118:119], v[2:3]
	v_mov_b64_e32 v[120:121], v[2:3]
	v_mov_b64_e32 v[126:127], v[2:3]
	v_mov_b64_e32 v[128:129], v[2:3]
	v_mov_b64_e32 v[122:123], v[2:3]
	v_mov_b64_e32 v[124:125], v[2:3]
	v_mov_b64_e32 v[114:115], v[2:3]
	v_mov_b64_e32 v[116:117], v[2:3]
	v_mov_b64_e32 v[110:111], v[2:3]
	v_mov_b64_e32 v[112:113], v[2:3]
	v_mov_b64_e32 v[106:107], v[2:3]
	v_mov_b64_e32 v[108:109], v[2:3]
	v_mov_b64_e32 v[102:103], v[2:3]
	v_mov_b64_e32 v[104:105], v[2:3]
	v_mov_b64_e32 v[94:95], v[2:3]
	v_mov_b64_e32 v[96:97], v[2:3]
	s_branch .LBB0_1492

;   __device__ __forceinline__ bool next(int i,AttnUnit&u)const{ if(i>=2)return false; const int s=vcu&3; u.bh=vcu>>2; u.qb=(i==0)?s:7-s; return true; }
;   __device__ __forceinline__ bool next(int,AttnUnit&u)const{ __syncthreads(); if(threadIdx.x==0)*slot=__hip_atomic_fetch_add(ctr,1u,__ATOMIC_RELAXED,__HIP_MEMORY_SCOPE_AGENT); __syncthreads(); const unsigned v=*slot; if(v>=512u)return false; u.qb=7-(int)(v>>6); u.bh=(int)(v&63u); return true; }
; template <class Epi, class Sched, bool ALIGN_EPI = false, bool SP2 = false>
; __device__ __forceinline__ void gemm_phase(PG8_LAS unsigned char* lds, const Gemm g, const Sched& S, const Epi& E) {
;     ...
;     for (;;) {
;         const bool has_next = S.next(ui + 1, nxt);
;         const char* nA = has_next ? (const char*)g.A + (size_t)nxt.pm * tstep : cA; const char* nB = has_next ? (const char*)g.Bt + (size_t)nxt.pn * tstep : cB;
;         for (int t = 0; t < nt; t += 2) {
;             const bool last = (t == nt - 2);
;             const char* a1 = cA + (size_t)(t + 1) * kstep;
;             const char* a2 = last ? nA : cA + (size_t)(t + 2) * kstep; const char* b2 = last ? nB : cB + (size_t)(t + 2) * kstep;
;             const char* a3 = a2 + kstep; const char* b3 = b2 + kstep;
;     ...
; #pragma unroll
;         for (int a = 0; a < 2; ++a)
; #pragma unroll
;             for (int b = 0; b < 2; ++b)
; #pragma unroll
;                 for (int m = 0; m < 4; ++m)
; #pragma unroll
;                     for (int n = 0; n < 2; ++n) acc[a][b][m][n] = (f32x4){0.f, 0.f, 0.f, 0.f};
;         cur = nxt; cA = nA; cB = nB; ++ui;
.LBB0_1627:
	s_ashr_i32 s23, s22, 31
	s_lshl_b64 s[2:3], s[22:23], 19
	s_add_u32 s24, s10, s2
	s_addc_u32 s25, s11, s3
	s_and_b64 s[2:3], s[6:7], exec
	s_cselect_b32 s23, s25, s15
	s_cselect_b32 s46, s24, s14
	s_ashr_i32 s21, s20, 31
	s_lshl_b64 s[2:3], s[20:21], 19
	s_add_u32 s28, s82, s2
	s_addc_u32 s29, s83, s3
	s_and_b64 s[2:3], s[6:7], exec
	s_cselect_b32 s21, s29, s35
	s_cselect_b32 s47, s28, s34
	s_add_u32 s36, s14, 0x40080
	s_addc_u32 s37, s15, 0
	s_add_u32 s34, s34, 0x100
	v_mov_b32_e32 v2, 0
	s_addc_u32 s35, s35, 0
	s_mov_b32 s48, -2
	v_mov_b32_e32 v3, v2
	v_mov_b64_e32 v[4:5], v[2:3]
	v_mov_b64_e32 v[6:7], v[2:3]
	v_mov_b64_e32 v[8:9], v[2:3]
	v_mov_b64_e32 v[18:19], v[2:3]
	v_mov_b64_e32 v[20:21], v[2:3]
	v_mov_b64_e32 v[22:23], v[2:3]
	v_mov_b64_e32 v[24:25], v[2:3]
	v_mov_b64_e32 v[34:35], v[2:3]
	v_mov_b64_e32 v[36:37], v[2:3]
	v_mov_b64_e32 v[38:39], v[2:3]
	v_mov_b64_e32 v[40:41], v[2:3]
	v_mov_b64_e32 v[50:51], v[2:3]
	v_mov_b64_e32 v[52:53], v[2:3]
	v_mov_b64_e32 v[54:55], v[2:3]
	v_mov_b64_e32 v[56:57], v[2:3]
	v_mov_b64_e32 v[10:11], v[2:3]
	v_mov_b64_e32 v[12:13], v[2:3]
	v_mov_b64_e32 v[14:15], v[2:3]
	v_mov_b64_e32 v[16:17], v[2:3]
	v_mov_b64_e32 v[26:27], v[2:3]
	v_mov_b64_e32 v[28:29], v[2:3]
	v_mov_b64_e32 v[30:31], v[2:3]
	v_mov_b64_e32 v[32:33], v[2:3]
	v_mov_b64_e32 v[42:43], v[2:3]
	v_mov_b64_e32 v[44:45], v[2:3]
	v_mov_b64_e32 v[46:47], v[2:3]
	v_mov_b64_e32 v[48:49], v[2:3]
	v_mov_b64_e32 v[58:59], v[2:3]
	v_mov_b64_e32 v[60:61], v[2:3]
	v_mov_b64_e32 v[62:63], v[2:3]
	v_mov_b64_e32 v[64:65], v[2:3]
	v_mov_b64_e32 v[66:67], v[2:3]
	v_mov_b64_e32 v[68:69], v[2:3]
	v_mov_b64_e32 v[70:71], v[2:3]
	v_mov_b64_e32 v[72:73], v[2:3]
	v_mov_b64_e32 v[82:83], v[2:3]
	v_mov_b64_e32 v[84:85], v[2:3]
	v_mov_b64_e32 v[86:87], v[2:3]
	v_mov_b64_e32 v[88:89], v[2:3]
	v_mov_b64_e32 v[98:99], v[2:3]
	v_mov_b64_e32 v[100:101], v[2:3]
	v_mov_b64_e32 v[102:103], v[2:3]
	v_mov_b64_e32 v[104:105], v[2:3]
	v_mov_b64_e32 v[114:115], v[2:3]
	v_mov_b64_e32 v[116:117], v[2:3]
	v_mov_b64_e32 v[118:119], v[2:3]
	v_mov_b64_e32 v[120:121], v[2:3]
	v_mov_b64_e32 v[74:75], v[2:3]
	v_mov_b64_e32 v[76:77], v[2:3]
	v_mov_b64_e32 v[78:79], v[2:3]
	v_mov_b64_e32 v[80:81], v[2:3]
	v_mov_b64_e32 v[90:91], v[2:3]
	v_mov_b64_e32 v[92:93], v[2:3]
	v_mov_b64_e32 v[94:95], v[2:3]
	v_mov_b64_e32 v[96:97], v[2:3]
	v_mov_b64_e32 v[106:107], v[2:3]
	v_mov_b64_e32 v[108:109], v[2:3]
	v_mov_b64_e32 v[110:111], v[2:3]
	v_mov_b64_e32 v[112:113], v[2:3]
	v_mov_b64_e32 v[122:123], v[2:3]
	v_mov_b64_e32 v[124:125], v[2:3]
	v_mov_b64_e32 v[126:127], v[2:3]
	v_mov_b64_e32 v[128:129], v[2:3]

; #define PG8_STAGE(bufoff, gbase, voff) do { _Pragma("unroll") for (int _i = 0; _i < 2; ++_i) \
;         __builtin_amdgcn_global_load_lds((const unsigned*)((const char*)(gbase) + (voff)[_i]), (PG8_LAS unsigned*)(lds + (bufoff) + ldsw + _i * 8192), 16, 0, 0); } while (0)
; #define PG8_LDA(dst, b, h) do { _Pragma("unroll") for (int m = 0; m < 4; ++m) _Pragma("unroll") for (int k = 0; k < 2; ++k) dst[m][k] = *(const PG8_LAS bf16x8*)(lds + PG8_SA(b, h) + aoff + m * 2048 + k * 1024); } while (0)
; #define PG8_LDB(dst, b, h) do { _Pragma("unroll") for (int n = 0; n < 2; ++n) _Pragma("unroll") for (int k = 0; k < 2; ++k) dst[n][k] = *(const PG8_LAS bf16x8*)(lds + PG8_SB(b, h) + boff + n * 2048 + k * 1024); } while (0)
; #define PG8_MMA(ai, bj, At, Bt) do { __builtin_amdgcn_s_setprio(1); _Pragma("unroll") for (int m = 0; m < 4; ++m) _Pragma("unroll") for (int n = 0; n < 2; ++n) _Pragma("unroll") for (int k = 0; k < 2; ++k) \
;         acc[ai][bj][m][n] = __builtin_amdgcn_mfma_f32_16x16x32_bf16(Bt[n][k], At[m][k], acc[ai][bj][m][n], 0, 0, 0); __builtin_amdgcn_s_setprio(0); } while (0)
; #define PG8_WAIT_V(n) asm volatile("s_waitcnt vmcnt(" #n ")" ::: "memory")
; #define PG8_BAR __builtin_amdgcn_s_barrier()
; template <class Epi, class Sched, bool ALIGN_EPI = false, bool SP2 = false>
; __device__ __forceinline__ void gemm_phase(PG8_LAS unsigned char* lds, const Gemm g, const Sched& S, const Epi& E) {
;     ...
;         for (int t = 0; t < nt; t += 2) {
;             const bool last = (t == nt - 2);
;             const char* a1 = cA + (size_t)(t + 1) * kstep;
;             const char* a2 = last ? nA : cA + (size_t)(t + 2) * kstep; const char* b2 = last ? nB : cB + (size_t)(t + 2) * kstep;
;             const char* a3 = a2 + kstep; const char* b3 = b2 + kstep;
;             if (last && has_next) S.a_ready(nxt);
;             if constexpr (SP2) {
;             PG8_LDB(B0, 0, 0); PG8_LDB(B1, 0, 1); PG8_SCHED; PG8_LDA(At, 0, 0); PG8_STAGE(PG8_SA(1, 1), a1 + hstep, voffA);
;             PG8_WAIT_V(8); PG8_WAIT_L(0); PG8_BAR; PG8_MMA(0, 0, At, B0); PG8_MMA(0, 1, At, B1); PG8_BAR; PG8_SCHED;
;             PG8_LDA(At, 0, 1); PG8_STAGE(PG8_SB(0, 0), b2, voffB); PG8_STAGE(PG8_SB(0, 1), b2 + hstep, voffB); PG8_STAGE(PG8_SA(0, 0), a2, voffA);
;             PG8_WAIT_V(8); PG8_WAIT_L(0); PG8_BAR; PG8_MMA(1, 0, At, B0); PG8_MMA(1, 1, At, B1); PG8_BAR; PG8_SCHED;
.LBB0_1706:
	v_add_u32_e32 v162, s39, v152
	ds_read_b128 v[154:157], v162
	ds_read_b128 v[158:161], v162 offset:1024
	ds_read_b128 v[166:169], v162 offset:2048
	ds_read_b128 v[170:173], v162 offset:3072
	v_add_u32_e32 v162, s40, v152
	s_add_u32 s2, s14, s20
	ds_read_b128 v[174:177], v162
	ds_read_b128 v[178:181], v162 offset:1024
	ds_read_b128 v[182:185], v162 offset:2048
	ds_read_b128 v[186:189], v162 offset:3072
	s_addc_u32 s3, s15, s21
	s_add_u32 s2, s2, 0x100
	s_addc_u32 s3, s3, 0
	s_add_u32 s47, s44, s20
	s_addc_u32 s48, s45, s21
	s_cmpk_eq_i32 s20, 0x1500
	s_cselect_b32 s23, s19, s3
	s_cselect_b32 s22, s18, s2
	s_cselect_b32 s3, s7, s48
	s_cselect_b32 s2, s6, s47
	v_lshl_add_u64 v[162:163], v[146:147], 0, s[20:21]
	s_add_i32 m0, s30, 0xc000
	ds_read_b128 v[190:193], v153
	ds_read_b128 v[194:197], v153 offset:1024
	ds_read_b128 v[198:201], v153 offset:2048
	ds_read_b128 v[202:205], v153 offset:3072
	ds_read_b128 v[206:209], v153 offset:4096
	ds_read_b128 v[210:213], v153 offset:5120
	ds_read_b128 v[214:217], v153 offset:6144
	ds_read_b128 v[218:221], v153 offset:7168
	global_load_lds_dwordx4 v[162:163], off
	v_lshl_add_u64 v[162:163], v[148:149], 0, s[20:21]
	s_add_i32 m0, s30, 0xe000
	s_nop 0
	global_load_lds_dwordx4 v[162:163], off
	s_waitcnt vmcnt(8)
	s_waitcnt lgkmcnt(0)
	s_barrier
	s_setprio 1
	s_waitcnt lgkmcnt(0)
	v_mfma_f32_16x16x32_bf16 v[70:73], v[154:157], v[190:193], v[70:73]
	v_mfma_f32_16x16x32_bf16 v[78:81], v[166:169], v[190:193], v[78:81]
	v_mfma_f32_16x16x32_bf16 v[94:97], v[154:157], v[198:201], v[94:97]
	v_mfma_f32_16x16x32_bf16 v[118:121], v[166:169], v[198:201], v[118:121]
	v_mfma_f32_16x16x32_bf16 v[106:109], v[154:157], v[206:209], v[106:109]
	v_mfma_f32_16x16x32_bf16 v[114:117], v[166:169], v[206:209], v[114:117]
	v_mfma_f32_16x16x32_bf16 v[122:125], v[154:157], v[214:217], v[122:125]
	v_mfma_f32_16x16x32_bf16 v[126:129], v[166:169], v[214:217], v[126:129]
	v_mfma_f32_16x16x32_bf16 v[70:73], v[158:161], v[194:197], v[70:73]
	v_mfma_f32_16x16x32_bf16 v[78:81], v[170:173], v[194:197], v[78:81]
	v_mfma_f32_16x16x32_bf16 v[94:97], v[158:161], v[202:205], v[94:97]
	v_mfma_f32_16x16x32_bf16 v[118:121], v[170:173], v[202:205], v[118:121]
	v_mfma_f32_16x16x32_bf16 v[106:109], v[158:161], v[210:213], v[106:109]
	v_mfma_f32_16x16x32_bf16 v[114:117], v[170:173], v[210:213], v[114:117]
	v_mfma_f32_16x16x32_bf16 v[122:125], v[158:161], v[218:221], v[122:125]
	v_mfma_f32_16x16x32_bf16 v[126:129], v[170:173], v[218:221], v[126:129]
	s_setprio 0
	s_setprio 1
	v_mfma_f32_16x16x32_bf16 v[66:69], v[174:177], v[190:193], v[66:69]
	v_mfma_f32_16x16x32_bf16 v[74:77], v[182:185], v[190:193], v[74:77]
	v_mfma_f32_16x16x32_bf16 v[82:85], v[174:177], v[198:201], v[82:85]
	v_mfma_f32_16x16x32_bf16 v[86:89], v[182:185], v[198:201], v[86:89]
	v_mfma_f32_16x16x32_bf16 v[90:93], v[174:177], v[206:209], v[90:93]
	v_mfma_f32_16x16x32_bf16 v[98:101], v[182:185], v[206:209], v[98:101]
	v_mfma_f32_16x16x32_bf16 v[102:105], v[174:177], v[214:217], v[102:105]
	v_mfma_f32_16x16x32_bf16 v[110:113], v[182:185], v[214:217], v[110:113]
	v_mfma_f32_16x16x32_bf16 v[66:69], v[178:181], v[194:197], v[66:69]
	v_mfma_f32_16x16x32_bf16 v[74:77], v[186:189], v[194:197], v[74:77]
	v_mfma_f32_16x16x32_bf16 v[82:85], v[178:181], v[202:205], v[82:85]
	v_mfma_f32_16x16x32_bf16 v[86:89], v[186:189], v[202:205], v[86:89]
	v_mfma_f32_16x16x32_bf16 v[90:93], v[178:181], v[210:213], v[90:93]
	v_mfma_f32_16x16x32_bf16 v[98:101], v[186:189], v[210:213], v[98:101]
	v_mfma_f32_16x16x32_bf16 v[102:105], v[178:181], v[218:221], v[102:105]
	v_mfma_f32_16x16x32_bf16 v[110:113], v[186:189], v[218:221], v[110:113]
	s_setprio 0
	s_barrier
	s_add_i32 s47, s39, s29
	v_lshl_add_u64 v[162:163], s[2:3], 0, v[132:133]
	s_mov_b32 m0, s47
	ds_read_b128 v[190:193], v153 offset:16384
	ds_read_b128 v[194:197], v153 offset:17408
	ds_read_b128 v[198:201], v153 offset:18432
	ds_read_b128 v[202:205], v153 offset:19456
	ds_read_b128 v[206:209], v153 offset:20480
	ds_read_b128 v[210:213], v153 offset:21504
	ds_read_b128 v[214:217], v153 offset:22528
	ds_read_b128 v[218:221], v153 offset:23552
	global_load_lds_dwordx4 v[162:163], off
	s_add_i32 m0, s47, 0x2000
	s_add_u32 s48, s2, 0xb0000
	v_lshl_add_u64 v[222:223], s[2:3], 0, v[136:137]
	s_addc_u32 s49, s3, 0
	s_add_i32 s47, s40, s29
	global_load_lds_dwordx4 v[222:223], off
	v_lshl_add_u64 v[224:225], s[48:49], 0, v[132:133]
	s_mov_b32 m0, s47
	v_lshl_add_u64 v[226:227], s[22:23], 0, v[134:135]
	global_load_lds_dwordx4 v[224:225], off
	v_lshl_add_u64 v[224:225], s[48:49], 0, v[136:137]
	s_add_i32 m0, s47, 0x2000
	s_nop 0
	global_load_lds_dwordx4 v[224:225], off
	v_lshl_add_u64 v[224:225], s[22:23], 0, v[130:131]
	s_mov_b32 m0, s30
	s_nop 0
	global_load_lds_dwordx4 v[224:225], off
	s_mov_b32 m0, s31
	s_nop 0
	global_load_lds_dwordx4 v[226:227], off
	s_waitcnt vmcnt(8)
	s_waitcnt lgkmcnt(0)
	s_barrier
; #define PG8_STAGE(bufoff, gbase, voff) do { _Pragma("unroll") for (int _i = 0; _i < 2; ++_i) \
;         __builtin_amdgcn_global_load_lds((const unsigned*)((const char*)(gbase) + (voff)[_i]), (PG8_LAS unsigned*)(lds + (bufoff) + ldsw + _i * 8192), 16, 0, 0); } while (0)
; #define PG8_LDA(dst, b, h) do { _Pragma("unroll") for (int m = 0; m < 4; ++m) _Pragma("unroll") for (int k = 0; k < 2; ++k) dst[m][k] = *(const PG8_LAS bf16x8*)(lds + PG8_SA(b, h) + aoff + m * 2048 + k * 1024); } while (0)
; #define PG8_LDB(dst, b, h) do { _Pragma("unroll") for (int n = 0; n < 2; ++n) _Pragma("unroll") for (int k = 0; k < 2; ++k) dst[n][k] = *(const PG8_LAS bf16x8*)(lds + PG8_SB(b, h) + boff + n * 2048 + k * 1024); } while (0)
; #define PG8_MMA(ai, bj, At, Bt) do { __builtin_amdgcn_s_setprio(1); _Pragma("unroll") for (int m = 0; m < 4; ++m) _Pragma("unroll") for (int n = 0; n < 2; ++n) _Pragma("unroll") for (int k = 0; k < 2; ++k) \
;         acc[ai][bj][m][n] = __builtin_amdgcn_mfma_f32_16x16x32_bf16(Bt[n][k], At[m][k], acc[ai][bj][m][n], 0, 0, 0); __builtin_amdgcn_s_setprio(0); } while (0)
; #define PG8_WAIT_V(n) asm volatile("s_waitcnt vmcnt(" #n ")" ::: "memory")
; #define PG8_WAIT_L(n) asm volatile("s_waitcnt lgkmcnt(" #n ")" ::: "memory")
; #define PG8_BAR __builtin_amdgcn_s_barrier()
; #define PG8_SCHED __builtin_amdgcn_sched_barrier(0)
; template <class Epi, class Sched, bool ALIGN_EPI = false, bool SP2 = false>
; __device__ __forceinline__ void gemm_phase(PG8_LAS unsigned char* lds, const Gemm g, const Sched& S, const Epi& E) {
;     ...
;             PG8_WAIT_V(8); PG8_WAIT_L(0); PG8_BAR; PG8_MMA(1, 0, At, B0); PG8_MMA(1, 1, At, B1); PG8_BAR; PG8_SCHED;
;             PG8_LDB(B0, 1, 0); PG8_LDB(B1, 1, 1); PG8_SCHED; PG8_LDA(At, 1, 0); PG8_STAGE(PG8_SA(0, 1), a2 + hstep, voffA);
;             PG8_WAIT_V(8); PG8_WAIT_L(0); PG8_BAR; PG8_MMA(0, 0, At, B0); PG8_MMA(0, 1, At, B1); PG8_BAR; PG8_SCHED;
	s_setprio 1
	s_waitcnt lgkmcnt(0)
	v_mfma_f32_16x16x32_bf16 v[62:65], v[154:157], v[190:193], v[62:65]
	v_mfma_f32_16x16x32_bf16 v[58:61], v[166:169], v[190:193], v[58:61]
	v_mfma_f32_16x16x32_bf16 v[46:49], v[154:157], v[198:201], v[46:49]
	v_mfma_f32_16x16x32_bf16 v[42:45], v[166:169], v[198:201], v[42:45]
	v_mfma_f32_16x16x32_bf16 v[30:33], v[154:157], v[206:209], v[30:33]
	v_mfma_f32_16x16x32_bf16 v[26:29], v[166:169], v[206:209], v[26:29]
	v_mfma_f32_16x16x32_bf16 v[14:17], v[154:157], v[214:217], v[14:17]
	v_mfma_f32_16x16x32_bf16 v[10:13], v[166:169], v[214:217], v[10:13]
	v_mfma_f32_16x16x32_bf16 v[62:65], v[158:161], v[194:197], v[62:65]
	v_mfma_f32_16x16x32_bf16 v[58:61], v[170:173], v[194:197], v[58:61]
	v_mfma_f32_16x16x32_bf16 v[46:49], v[158:161], v[202:205], v[46:49]
	v_mfma_f32_16x16x32_bf16 v[42:45], v[170:173], v[202:205], v[42:45]
	v_mfma_f32_16x16x32_bf16 v[30:33], v[158:161], v[210:213], v[30:33]
	v_mfma_f32_16x16x32_bf16 v[26:29], v[170:173], v[210:213], v[26:29]
	v_mfma_f32_16x16x32_bf16 v[14:17], v[158:161], v[218:221], v[14:17]
	v_mfma_f32_16x16x32_bf16 v[10:13], v[170:173], v[218:221], v[10:13]
	s_setprio 0
	s_setprio 1
	v_mfma_f32_16x16x32_bf16 v[54:57], v[174:177], v[190:193], v[54:57]
	v_mfma_f32_16x16x32_bf16 v[50:53], v[182:185], v[190:193], v[50:53]
	v_mfma_f32_16x16x32_bf16 v[38:41], v[174:177], v[198:201], v[38:41]
	v_mfma_f32_16x16x32_bf16 v[34:37], v[182:185], v[198:201], v[34:37]
	v_mfma_f32_16x16x32_bf16 v[22:25], v[174:177], v[206:209], v[22:25]
	v_mfma_f32_16x16x32_bf16 v[18:21], v[182:185], v[206:209], v[18:21]
	v_mfma_f32_16x16x32_bf16 v[6:9], v[174:177], v[214:217], v[6:9]
	v_mfma_f32_16x16x32_bf16 v[2:5], v[182:185], v[214:217], v[2:5]
	v_mfma_f32_16x16x32_bf16 v[54:57], v[178:181], v[194:197], v[54:57]
	v_mfma_f32_16x16x32_bf16 v[50:53], v[186:189], v[194:197], v[50:53]
	v_mfma_f32_16x16x32_bf16 v[38:41], v[178:181], v[202:205], v[38:41]
	v_mfma_f32_16x16x32_bf16 v[34:37], v[186:189], v[202:205], v[34:37]
	v_mfma_f32_16x16x32_bf16 v[22:25], v[178:181], v[210:213], v[22:25]
	v_mfma_f32_16x16x32_bf16 v[18:21], v[186:189], v[210:213], v[18:21]
	v_mfma_f32_16x16x32_bf16 v[6:9], v[178:181], v[218:221], v[6:9]
	v_mfma_f32_16x16x32_bf16 v[2:5], v[186:189], v[218:221], v[2:5]
	s_setprio 0
	s_barrier
	s_add_i32 s47, 0, 0x18000
	v_add_u32_e32 v165, s47, v152
	s_add_i32 s48, 0, 0x1c000
	ds_read_b128 v[154:157], v165
	ds_read_b128 v[158:161], v165 offset:1024
	ds_read_b128 v[166:169], v165 offset:2048
	ds_read_b128 v[170:173], v165 offset:3072
	v_add_u32_e32 v165, s48, v152
	ds_read_b128 v[174:177], v165
	ds_read_b128 v[178:181], v165 offset:1024
	ds_read_b128 v[182:185], v165 offset:2048
	ds_read_b128 v[186:189], v165 offset:3072
	s_add_u32 s22, s22, 0xb0000
	s_addc_u32 s23, s23, 0
	s_mov_b32 m0, s33
	v_lshl_add_u64 v[228:229], s[22:23], 0, v[130:131]
	ds_read_b128 v[190:193], v153 offset:32768
	ds_read_b128 v[194:197], v153 offset:33792
	ds_read_b128 v[198:201], v153 offset:34816
	ds_read_b128 v[202:205], v153 offset:35840
	ds_read_b128 v[206:209], v153 offset:36864
	ds_read_b128 v[210:213], v153 offset:37888
	ds_read_b128 v[214:217], v153 offset:38912
	ds_read_b128 v[218:221], v153 offset:39936
	global_load_lds_dwordx4 v[228:229], off
	v_lshl_add_u64 v[228:229], s[22:23], 0, v[134:135]
	s_mov_b32 m0, s34
	s_nop 0
	global_load_lds_dwordx4 v[228:229], off
	s_waitcnt vmcnt(8)
	s_waitcnt lgkmcnt(0)
	s_barrier
	s_setprio 1
	s_waitcnt lgkmcnt(0)
	v_mfma_f32_16x16x32_bf16 v[70:73], v[154:157], v[190:193], v[70:73]
	v_mfma_f32_16x16x32_bf16 v[78:81], v[166:169], v[190:193], v[78:81]
	v_mfma_f32_16x16x32_bf16 v[94:97], v[154:157], v[198:201], v[94:97]
	v_mfma_f32_16x16x32_bf16 v[118:121], v[166:169], v[198:201], v[118:121]
	v_mfma_f32_16x16x32_bf16 v[106:109], v[154:157], v[206:209], v[106:109]
	v_mfma_f32_16x16x32_bf16 v[114:117], v[166:169], v[206:209], v[114:117]
	v_mfma_f32_16x16x32_bf16 v[122:125], v[154:157], v[214:217], v[122:125]
	v_mfma_f32_16x16x32_bf16 v[126:129], v[166:169], v[214:217], v[126:129]
	v_mfma_f32_16x16x32_bf16 v[70:73], v[158:161], v[194:197], v[70:73]
	v_mfma_f32_16x16x32_bf16 v[78:81], v[170:173], v[194:197], v[78:81]
	v_mfma_f32_16x16x32_bf16 v[94:97], v[158:161], v[202:205], v[94:97]
	v_mfma_f32_16x16x32_bf16 v[118:121], v[170:173], v[202:205], v[118:121]
	v_mfma_f32_16x16x32_bf16 v[106:109], v[158:161], v[210:213], v[106:109]
	v_mfma_f32_16x16x32_bf16 v[114:117], v[170:173], v[210:213], v[114:117]
	v_mfma_f32_16x16x32_bf16 v[122:125], v[158:161], v[218:221], v[122:125]
	v_mfma_f32_16x16x32_bf16 v[126:129], v[170:173], v[218:221], v[126:129]
	s_setprio 0
	s_setprio 1
	v_mfma_f32_16x16x32_bf16 v[66:69], v[174:177], v[190:193], v[66:69]
	v_mfma_f32_16x16x32_bf16 v[74:77], v[182:185], v[190:193], v[74:77]
	v_mfma_f32_16x16x32_bf16 v[82:85], v[174:177], v[198:201], v[82:85]
	v_mfma_f32_16x16x32_bf16 v[86:89], v[182:185], v[198:201], v[86:89]
	v_mfma_f32_16x16x32_bf16 v[90:93], v[174:177], v[206:209], v[90:93]
	v_mfma_f32_16x16x32_bf16 v[98:101], v[182:185], v[206:209], v[98:101]
	v_mfma_f32_16x16x32_bf16 v[102:105], v[174:177], v[214:217], v[102:105]
	v_mfma_f32_16x16x32_bf16 v[110:113], v[182:185], v[214:217], v[110:113]
	v_mfma_f32_16x16x32_bf16 v[66:69], v[178:181], v[194:197], v[66:69]
	v_mfma_f32_16x16x32_bf16 v[74:77], v[186:189], v[194:197], v[74:77]
	v_mfma_f32_16x16x32_bf16 v[82:85], v[178:181], v[202:205], v[82:85]
	v_mfma_f32_16x16x32_bf16 v[86:89], v[186:189], v[202:205], v[86:89]
	v_mfma_f32_16x16x32_bf16 v[90:93], v[178:181], v[210:213], v[90:93]
	v_mfma_f32_16x16x32_bf16 v[98:101], v[186:189], v[210:213], v[98:101]
	v_mfma_f32_16x16x32_bf16 v[102:105], v[178:181], v[218:221], v[102:105]
	v_mfma_f32_16x16x32_bf16 v[110:113], v[186:189], v[218:221], v[110:113]
	s_setprio 0
	s_barrier
; #define PG8_STAGE(bufoff, gbase, voff) do { _Pragma("unroll") for (int _i = 0; _i < 2; ++_i) \
;         __builtin_amdgcn_global_load_lds((const unsigned*)((const char*)(gbase) + (voff)[_i]), (PG8_LAS unsigned*)(lds + (bufoff) + ldsw + _i * 8192), 16, 0, 0); } while (0)
; #define PG8_LDA(dst, b, h) do { _Pragma("unroll") for (int m = 0; m < 4; ++m) _Pragma("unroll") for (int k = 0; k < 2; ++k) dst[m][k] = *(const PG8_LAS bf16x8*)(lds + PG8_SA(b, h) + aoff + m * 2048 + k * 1024); } while (0)
; #define PG8_MMA(ai, bj, At, Bt) do { __builtin_amdgcn_s_setprio(1); _Pragma("unroll") for (int m = 0; m < 4; ++m) _Pragma("unroll") for (int n = 0; n < 2; ++n) _Pragma("unroll") for (int k = 0; k < 2; ++k) \
;         acc[ai][bj][m][n] = __builtin_amdgcn_mfma_f32_16x16x32_bf16(Bt[n][k], At[m][k], acc[ai][bj][m][n], 0, 0, 0); __builtin_amdgcn_s_setprio(0); } while (0)
; #define PG8_WAIT_V(n) asm volatile("s_waitcnt vmcnt(" #n ")" ::: "memory")
; #define PG8_WAIT_L(n) asm volatile("s_waitcnt lgkmcnt(" #n ")" ::: "memory")
; #define PG8_BAR __builtin_amdgcn_s_barrier()
; #define PG8_SCHED __builtin_amdgcn_sched_barrier(0)
; template <class Epi, class Sched, bool ALIGN_EPI = false, bool SP2 = false>
; __device__ __forceinline__ void gemm_phase(PG8_LAS unsigned char* lds, const Gemm g, const Sched& S, const Epi& E) {
;     ...
;             PG8_LDA(At, 1, 1); PG8_STAGE(PG8_SB(1, 0), b3, voffB); PG8_STAGE(PG8_SB(1, 1), b3 + hstep, voffB); PG8_STAGE(PG8_SA(1, 0), a3, voffA);
;             PG8_WAIT_V(8); PG8_WAIT_L(0); PG8_BAR; PG8_MMA(1, 0, At, B0); PG8_MMA(1, 1, At, B1); PG8_BAR; PG8_SCHED;
;     ...
;         if (!has_next) break;
; #pragma unroll
;         for (int a = 0; a < 2; ++a)
; #pragma unroll
;             for (int b = 0; b < 2; ++b)
; #pragma unroll
;                 for (int m = 0; m < 4; ++m)
; #pragma unroll
;                     for (int n = 0; n < 2; ++n) acc[a][b][m][n] = (f32x4){0.f, 0.f, 0.f, 0.f};
;         cur = nxt; cA = nA; cB = nB; ++ui;
	s_add_i32 s22, s47, s29
	v_lshl_add_u64 v[162:163], v[162:163], 0, s[16:17]
	s_mov_b32 m0, s22
	ds_read_b128 v[190:193], v153 offset:49152
	ds_read_b128 v[194:197], v153 offset:50176
	ds_read_b128 v[198:201], v153 offset:51200
	ds_read_b128 v[202:205], v153 offset:52224
	ds_read_b128 v[206:209], v153 offset:53248
	ds_read_b128 v[210:213], v153 offset:54272
	ds_read_b128 v[214:217], v153 offset:55296
	ds_read_b128 v[218:221], v153 offset:56320
	global_load_lds_dwordx4 v[162:163], off
	s_add_i32 m0, s22, 0x2000
	s_add_u32 s2, s2, 0xb0080
	v_lshl_add_u64 v[162:163], v[222:223], 0, s[16:17]
	s_addc_u32 s3, s3, 0
	s_add_i32 s22, s48, s29
	global_load_lds_dwordx4 v[162:163], off
	v_lshl_add_u64 v[162:163], s[2:3], 0, v[132:133]
	s_mov_b32 m0, s22
	s_nop 0
	global_load_lds_dwordx4 v[162:163], off
	v_lshl_add_u64 v[162:163], s[2:3], 0, v[136:137]
	s_add_i32 m0, s22, 0x2000
	s_nop 0
	global_load_lds_dwordx4 v[162:163], off
	v_lshl_add_u64 v[162:163], v[224:225], 0, s[16:17]
	s_mov_b32 m0, s37
	s_nop 0
	global_load_lds_dwordx4 v[162:163], off
	v_lshl_add_u64 v[162:163], v[226:227], 0, s[16:17]
	s_mov_b32 m0, s38
	s_nop 0
	global_load_lds_dwordx4 v[162:163], off
	s_waitcnt vmcnt(8)
	s_waitcnt lgkmcnt(0)
	s_barrier
	s_setprio 1
	s_waitcnt lgkmcnt(0)
	v_mfma_f32_16x16x32_bf16 v[62:65], v[154:157], v[190:193], v[62:65]
	v_mfma_f32_16x16x32_bf16 v[58:61], v[166:169], v[190:193], v[58:61]
	v_mfma_f32_16x16x32_bf16 v[46:49], v[154:157], v[198:201], v[46:49]
	v_mfma_f32_16x16x32_bf16 v[42:45], v[166:169], v[198:201], v[42:45]
	v_mfma_f32_16x16x32_bf16 v[30:33], v[154:157], v[206:209], v[30:33]
	v_mfma_f32_16x16x32_bf16 v[26:29], v[166:169], v[206:209], v[26:29]
	v_mfma_f32_16x16x32_bf16 v[14:17], v[154:157], v[214:217], v[14:17]
	v_mfma_f32_16x16x32_bf16 v[10:13], v[166:169], v[214:217], v[10:13]
	v_mfma_f32_16x16x32_bf16 v[62:65], v[158:161], v[194:197], v[62:65]
	v_mfma_f32_16x16x32_bf16 v[58:61], v[170:173], v[194:197], v[58:61]
	v_mfma_f32_16x16x32_bf16 v[46:49], v[158:161], v[202:205], v[46:49]
	v_mfma_f32_16x16x32_bf16 v[42:45], v[170:173], v[202:205], v[42:45]
	v_mfma_f32_16x16x32_bf16 v[30:33], v[158:161], v[210:213], v[30:33]
	v_mfma_f32_16x16x32_bf16 v[26:29], v[170:173], v[210:213], v[26:29]
	v_mfma_f32_16x16x32_bf16 v[14:17], v[158:161], v[218:221], v[14:17]
	v_mfma_f32_16x16x32_bf16 v[10:13], v[170:173], v[218:221], v[10:13]
	s_setprio 0
	s_setprio 1
	v_mfma_f32_16x16x32_bf16 v[54:57], v[174:177], v[190:193], v[54:57]
	v_mfma_f32_16x16x32_bf16 v[50:53], v[182:185], v[190:193], v[50:53]
	v_mfma_f32_16x16x32_bf16 v[38:41], v[174:177], v[198:201], v[38:41]
	v_mfma_f32_16x16x32_bf16 v[34:37], v[182:185], v[198:201], v[34:37]
	v_mfma_f32_16x16x32_bf16 v[22:25], v[174:177], v[206:209], v[22:25]
	v_mfma_f32_16x16x32_bf16 v[18:21], v[182:185], v[206:209], v[18:21]
	v_mfma_f32_16x16x32_bf16 v[6:9], v[174:177], v[214:217], v[6:9]
	v_mfma_f32_16x16x32_bf16 v[2:5], v[182:185], v[214:217], v[2:5]
	v_mfma_f32_16x16x32_bf16 v[54:57], v[178:181], v[194:197], v[54:57]
	v_mfma_f32_16x16x32_bf16 v[50:53], v[186:189], v[194:197], v[50:53]
	v_mfma_f32_16x16x32_bf16 v[38:41], v[178:181], v[202:205], v[38:41]
	v_mfma_f32_16x16x32_bf16 v[34:37], v[186:189], v[202:205], v[34:37]
	v_mfma_f32_16x16x32_bf16 v[22:25], v[178:181], v[210:213], v[22:25]
	v_mfma_f32_16x16x32_bf16 v[18:21], v[186:189], v[210:213], v[18:21]
	v_mfma_f32_16x16x32_bf16 v[6:9], v[178:181], v[218:221], v[6:9]
	v_mfma_f32_16x16x32_bf16 v[2:5], v[186:189], v[218:221], v[2:5]
	s_setprio 0
	s_barrier
	s_add_i32 s46, s46, 2
	s_add_u32 s20, s20, 0x100
	s_addc_u32 s21, s21, 0
	s_cmp_gt_u32 s46, 41
	s_cbranch_scc0 .LBB0_1706
	s_add_u32 s2, s44, 0xffffff00
	s_addc_u32 s3, s45, -1
	s_and_b64 vcc, exec, s[4:5]
	s_cbranch_vccnz .LBB0_1709
	v_mov_b32_e32 v2, 0
	s_mov_b32 s12, s41
	s_mov_b32 s25, s42
	s_mov_b64 s[14:15], s[18:19]
	s_mov_b32 s36, s43
	v_mov_b32_e32 v3, v2
	v_mov_b64_e32 v[4:5], v[2:3]
	v_mov_b64_e32 v[6:7], v[2:3]
	v_mov_b64_e32 v[8:9], v[2:3]
	v_mov_b64_e32 v[18:19], v[2:3]
	v_mov_b64_e32 v[20:21], v[2:3]
	v_mov_b64_e32 v[22:23], v[2:3]
	v_mov_b64_e32 v[24:25], v[2:3]
	v_mov_b64_e32 v[34:35], v[2:3]
	v_mov_b64_e32 v[36:37], v[2:3]
	v_mov_b64_e32 v[38:39], v[2:3]
	v_mov_b64_e32 v[40:41], v[2:3]
	v_mov_b64_e32 v[50:51], v[2:3]
	v_mov_b64_e32 v[52:53], v[2:3]
	v_mov_b64_e32 v[54:55], v[2:3]
	v_mov_b64_e32 v[56:57], v[2:3]
	v_mov_b64_e32 v[10:11], v[2:3]
	v_mov_b64_e32 v[12:13], v[2:3]
	v_mov_b64_e32 v[14:15], v[2:3]
	v_mov_b64_e32 v[16:17], v[2:3]
	v_mov_b64_e32 v[26:27], v[2:3]
	v_mov_b64_e32 v[28:29], v[2:3]
	v_mov_b64_e32 v[30:31], v[2:3]
	v_mov_b64_e32 v[32:33], v[2:3]
	v_mov_b64_e32 v[42:43], v[2:3]
	v_mov_b64_e32 v[44:45], v[2:3]
	v_mov_b64_e32 v[46:47], v[2:3]
	v_mov_b64_e32 v[48:49], v[2:3]
	v_mov_b64_e32 v[58:59], v[2:3]
	v_mov_b64_e32 v[60:61], v[2:3]
	v_mov_b64_e32 v[62:63], v[2:3]
	v_mov_b64_e32 v[64:65], v[2:3]
	v_mov_b64_e32 v[110:111], v[2:3]
	v_mov_b64_e32 v[112:113], v[2:3]
	v_mov_b64_e32 v[102:103], v[2:3]
	v_mov_b64_e32 v[104:105], v[2:3]
	v_mov_b64_e32 v[98:99], v[2:3]
	v_mov_b64_e32 v[100:101], v[2:3]
	v_mov_b64_e32 v[90:91], v[2:3]
	v_mov_b64_e32 v[92:93], v[2:3]
	v_mov_b64_e32 v[86:87], v[2:3]
	v_mov_b64_e32 v[88:89], v[2:3]
	v_mov_b64_e32 v[82:83], v[2:3]
	v_mov_b64_e32 v[84:85], v[2:3]
	v_mov_b64_e32 v[74:75], v[2:3]
	v_mov_b64_e32 v[76:77], v[2:3]
	v_mov_b64_e32 v[66:67], v[2:3]
	v_mov_b64_e32 v[68:69], v[2:3]
	v_mov_b64_e32 v[126:127], v[2:3]
	v_mov_b64_e32 v[128:129], v[2:3]
	v_mov_b64_e32 v[122:123], v[2:3]
	v_mov_b64_e32 v[124:125], v[2:3]
	v_mov_b64_e32 v[114:115], v[2:3]
	v_mov_b64_e32 v[116:117], v[2:3]
	v_mov_b64_e32 v[106:107], v[2:3]
	v_mov_b64_e32 v[108:109], v[2:3]
	v_mov_b64_e32 v[118:119], v[2:3]
	v_mov_b64_e32 v[120:121], v[2:3]
	v_mov_b64_e32 v[94:95], v[2:3]
	v_mov_b64_e32 v[96:97], v[2:3]
	v_mov_b64_e32 v[78:79], v[2:3]
	v_mov_b64_e32 v[80:81], v[2:3]
	v_mov_b64_e32 v[70:71], v[2:3]
	v_mov_b64_e32 v[72:73], v[2:3]
	s_andn2_b64 vcc, exec, s[0:1]
	s_cbranch_vccnz .LBB0_1710
	s_branch .LBB0_1711
